# code placement: every GEMM K-loop head padded onto an 8-byte boundary (a 4-byte shift of one K-loop cost 2.7 % in a repeat-region probe); on top of the P4 split, P3 carry move and 35/33 attention re-d
# baseline (speedup 1.0000x reference)
; template <class Epi, class Sched, bool ALIGN_EPI = false, bool SP2 = false, bool GRP = false>
; __device__ __forceinline__ void gemm_phase(PG8_LAS unsigned char* lds, const Gemm g, const Sched& S, const Epi& E) {
;     ...
;         for (int t = 0; t < nt; t += 2) {
;             const bool last = (t == nt - 2);
;             const char* a1 = cA + (size_t)(t + 1) * kstep;
;             const char* a2 = last ? nA : cA + (size_t)(t + 2) * kstep; const char* b2 = last ? nB : cB + (size_t)(t + 2) * kstep;
;             const char* a3 = a2 + kstep; const char* b3 = b2 + kstep;
;     ...
; #pragma unroll
;         for (int a = 0; a < 2; ++a)
; #pragma unroll
;             for (int b = 0; b < 2; ++b)
; #pragma unroll
;                 for (int m = 0; m < 4; ++m)
; #pragma unroll
;                     for (int n = 0; n < 2; ++n) acc[a][b][m][n] = (f32x4){0.f, 0.f, 0.f, 0.f};
;         cur = nxt; cA = nA; cB = nB; ++ui;
.LBB0_296:
	v_mov_b32_e32 v125, 0
	s_andn2_b64 vcc, exec, s[18:19]
	v_mov_b32_e32 v124, v125
	v_mov_b32_e32 v123, v125
	v_mov_b32_e32 v122, v125
	v_mov_b32_e32 v129, v125
	v_mov_b32_e32 v128, v125
	v_mov_b32_e32 v127, v125
	v_mov_b32_e32 v126, v125
	v_mov_b32_e32 v113, v125
	v_mov_b32_e32 v112, v125
	v_mov_b32_e32 v111, v125
	v_mov_b32_e32 v110, v125
	v_mov_b32_e32 v109, v125
	v_mov_b32_e32 v108, v125
	v_mov_b32_e32 v107, v125
	v_mov_b32_e32 v106, v125
	v_mov_b32_e32 v97, v125
	v_mov_b32_e32 v96, v125
	v_mov_b32_e32 v95, v125
	v_mov_b32_e32 v94, v125
	v_mov_b32_e32 v93, v125
	v_mov_b32_e32 v92, v125
	v_mov_b32_e32 v91, v125
	v_mov_b32_e32 v90, v125
	v_mov_b32_e32 v81, v125
	v_mov_b32_e32 v80, v125
	v_mov_b32_e32 v79, v125
	v_mov_b32_e32 v78, v125
	v_mov_b32_e32 v77, v125
	v_mov_b32_e32 v76, v125
	v_mov_b32_e32 v75, v125
	v_mov_b32_e32 v74, v125
	v_mov_b32_e32 v121, v125
	v_mov_b32_e32 v120, v125
	v_mov_b32_e32 v119, v125
	v_mov_b32_e32 v118, v125
	v_mov_b32_e32 v117, v125
	v_mov_b32_e32 v116, v125
	v_mov_b32_e32 v115, v125
	v_mov_b32_e32 v114, v125
	v_mov_b32_e32 v105, v125
	v_mov_b32_e32 v104, v125
	v_mov_b32_e32 v103, v125
	v_mov_b32_e32 v102, v125
	v_mov_b32_e32 v101, v125
	v_mov_b32_e32 v100, v125
	v_mov_b32_e32 v99, v125
	v_mov_b32_e32 v98, v125
	v_mov_b32_e32 v89, v125
	v_mov_b32_e32 v88, v125
	v_mov_b32_e32 v87, v125
	v_mov_b32_e32 v86, v125
	v_mov_b32_e32 v85, v125
	v_mov_b32_e32 v84, v125
	v_mov_b32_e32 v83, v125
	v_mov_b32_e32 v82, v125
	v_mov_b32_e32 v73, v125
	v_mov_b32_e32 v72, v125
	v_mov_b32_e32 v71, v125
	v_mov_b32_e32 v70, v125
	v_mov_b32_e32 v69, v125
	v_mov_b32_e32 v68, v125
	v_mov_b32_e32 v67, v125
	v_mov_b32_e32 v66, v125
	v_mov_b32_e32 v65, v125
	v_mov_b32_e32 v64, v125
	v_mov_b32_e32 v63, v125
	v_mov_b32_e32 v62, v125
	v_mov_b32_e32 v61, v125
	v_mov_b32_e32 v60, v125
	v_mov_b32_e32 v59, v125
	v_mov_b32_e32 v58, v125
	v_mov_b32_e32 v49, v125
	v_mov_b32_e32 v48, v125
	v_mov_b32_e32 v47, v125
	v_mov_b32_e32 v46, v125
	v_mov_b32_e32 v45, v125
	v_mov_b32_e32 v44, v125
	v_mov_b32_e32 v43, v125
	v_mov_b32_e32 v42, v125
	v_mov_b32_e32 v33, v125
	v_mov_b32_e32 v32, v125
	v_mov_b32_e32 v31, v125
	v_mov_b32_e32 v30, v125
	v_mov_b32_e32 v29, v125
	v_mov_b32_e32 v28, v125
	v_mov_b32_e32 v27, v125
	v_mov_b32_e32 v26, v125
	v_mov_b32_e32 v17, v125
	v_mov_b32_e32 v16, v125
	v_mov_b32_e32 v15, v125
	v_mov_b32_e32 v14, v125
	v_mov_b32_e32 v13, v125
	v_mov_b32_e32 v12, v125
	v_mov_b32_e32 v11, v125
	v_mov_b32_e32 v10, v125
	v_mov_b32_e32 v57, v125
	v_mov_b32_e32 v56, v125
	v_mov_b32_e32 v55, v125
	v_mov_b32_e32 v54, v125
	v_mov_b32_e32 v53, v125
	v_mov_b32_e32 v52, v125
	v_mov_b32_e32 v51, v125
	v_mov_b32_e32 v50, v125
	v_mov_b32_e32 v41, v125
	v_mov_b32_e32 v40, v125
	v_mov_b32_e32 v39, v125
	v_mov_b32_e32 v38, v125
	v_mov_b32_e32 v37, v125
	v_mov_b32_e32 v36, v125
	v_mov_b32_e32 v35, v125
	v_mov_b32_e32 v34, v125
	v_mov_b32_e32 v25, v125
	v_mov_b32_e32 v24, v125
	v_mov_b32_e32 v23, v125
	v_mov_b32_e32 v22, v125
	v_mov_b32_e32 v21, v125
	v_mov_b32_e32 v20, v125
	v_mov_b32_e32 v19, v125
	v_mov_b32_e32 v18, v125
	v_mov_b32_e32 v9, v125
	v_mov_b32_e32 v8, v125
	v_mov_b32_e32 v7, v125
	v_mov_b32_e32 v6, v125
	v_mov_b32_e32 v5, v125
	v_mov_b32_e32 v4, v125
	v_mov_b32_e32 v3, v125
	v_mov_b32_e32 v2, v125
	s_cbranch_vccnz .LBB0_299
	s_add_u32 s26, s26, 0x80
	s_addc_u32 s27, s27, 0
	s_add_u32 s40, s28, 0x100
	v_mov_b32_e32 v2, 0
	s_addc_u32 s41, s29, 0
	s_mov_b32 s3, 0
	v_mov_b32_e32 v3, v2
	v_mov_b32_e32 v4, v2
	v_mov_b32_e32 v5, v2
	v_mov_b32_e32 v6, v2
	v_mov_b32_e32 v7, v2
	v_mov_b32_e32 v8, v2
	v_mov_b32_e32 v9, v2
	v_mov_b32_e32 v18, v2
	v_mov_b32_e32 v19, v2
	v_mov_b32_e32 v20, v2
	v_mov_b32_e32 v21, v2
	v_mov_b32_e32 v22, v2
	v_mov_b32_e32 v23, v2
	v_mov_b32_e32 v24, v2
	v_mov_b32_e32 v25, v2
	v_mov_b32_e32 v34, v2
	v_mov_b32_e32 v35, v2
	v_mov_b32_e32 v36, v2
	v_mov_b32_e32 v37, v2
	v_mov_b32_e32 v38, v2
	v_mov_b32_e32 v39, v2
	v_mov_b32_e32 v40, v2
	v_mov_b32_e32 v41, v2
	v_mov_b32_e32 v50, v2
	v_mov_b32_e32 v51, v2
	v_mov_b32_e32 v52, v2
	v_mov_b32_e32 v53, v2
	v_mov_b32_e32 v54, v2
	v_mov_b32_e32 v55, v2
	v_mov_b32_e32 v56, v2
	v_mov_b32_e32 v57, v2
	v_mov_b32_e32 v10, v2
	v_mov_b32_e32 v11, v2
	v_mov_b32_e32 v12, v2
	v_mov_b32_e32 v13, v2
	v_mov_b32_e32 v14, v2
	v_mov_b32_e32 v15, v2
	v_mov_b32_e32 v16, v2
	v_mov_b32_e32 v17, v2
	v_mov_b32_e32 v26, v2
	v_mov_b32_e32 v27, v2
	v_mov_b32_e32 v28, v2
	v_mov_b32_e32 v29, v2
	v_mov_b32_e32 v30, v2
	v_mov_b32_e32 v31, v2
	v_mov_b32_e32 v32, v2
	v_mov_b32_e32 v33, v2
	v_mov_b32_e32 v42, v2
	v_mov_b32_e32 v43, v2
	v_mov_b32_e32 v44, v2
	v_mov_b32_e32 v45, v2
	v_mov_b32_e32 v46, v2
	v_mov_b32_e32 v47, v2
	v_mov_b32_e32 v48, v2
	v_mov_b32_e32 v49, v2
	v_mov_b32_e32 v58, v2
	v_mov_b32_e32 v59, v2
	v_mov_b32_e32 v60, v2
	v_mov_b32_e32 v61, v2
	v_mov_b32_e32 v62, v2
	v_mov_b32_e32 v63, v2
	v_mov_b32_e32 v64, v2
	v_mov_b32_e32 v65, v2
	v_mov_b32_e32 v66, v2
	v_mov_b32_e32 v67, v2
	v_mov_b32_e32 v68, v2
	v_mov_b32_e32 v69, v2
	v_mov_b32_e32 v70, v2
	v_mov_b32_e32 v71, v2
	v_mov_b32_e32 v72, v2
	v_mov_b32_e32 v73, v2
	v_mov_b32_e32 v82, v2
	v_mov_b32_e32 v83, v2
	v_mov_b32_e32 v84, v2
	v_mov_b32_e32 v85, v2
	v_mov_b32_e32 v86, v2
	v_mov_b32_e32 v87, v2
	v_mov_b32_e32 v88, v2
	v_mov_b32_e32 v89, v2
	v_mov_b32_e32 v98, v2
	v_mov_b32_e32 v99, v2
	v_mov_b32_e32 v100, v2
	v_mov_b32_e32 v101, v2
	v_mov_b32_e32 v102, v2
	v_mov_b32_e32 v103, v2
	v_mov_b32_e32 v104, v2
	v_mov_b32_e32 v105, v2
	v_mov_b32_e32 v114, v2
	v_mov_b32_e32 v115, v2
	v_mov_b32_e32 v116, v2
	v_mov_b32_e32 v117, v2
	v_mov_b32_e32 v118, v2
	v_mov_b32_e32 v119, v2
	v_mov_b32_e32 v120, v2
	v_mov_b32_e32 v121, v2
	v_mov_b32_e32 v74, v2
	v_mov_b32_e32 v75, v2
	v_mov_b32_e32 v76, v2
	v_mov_b32_e32 v77, v2
	v_mov_b32_e32 v78, v2
	v_mov_b32_e32 v79, v2
	v_mov_b32_e32 v80, v2
	v_mov_b32_e32 v81, v2
	v_mov_b32_e32 v90, v2
	v_mov_b32_e32 v91, v2
	v_mov_b32_e32 v92, v2
	v_mov_b32_e32 v93, v2
	v_mov_b32_e32 v94, v2
	v_mov_b32_e32 v95, v2
	v_mov_b32_e32 v96, v2
	v_mov_b32_e32 v97, v2
	v_mov_b32_e32 v106, v2
	v_mov_b32_e32 v107, v2
	v_mov_b32_e32 v108, v2
	v_mov_b32_e32 v109, v2
	v_mov_b32_e32 v110, v2
	v_mov_b32_e32 v111, v2
	v_mov_b32_e32 v112, v2
	v_mov_b32_e32 v113, v2
	v_mov_b32_e32 v126, v2
	v_mov_b32_e32 v127, v2
	v_mov_b32_e32 v128, v2
	v_mov_b32_e32 v129, v2
	v_mov_b32_e32 v122, v2
	v_mov_b32_e32 v123, v2
	v_mov_b32_e32 v124, v2
	v_mov_b32_e32 v125, v2
	s_nop 0

; template <class Epi, class Sched, bool ALIGN_EPI = false, bool SP2 = false, bool GRP = false>
; __device__ __forceinline__ void gemm_phase(PG8_LAS unsigned char* lds, const Gemm g, const Sched& S, const Epi& E) {
;     ...
;         for (int t = 0; t < nt; t += 2) {
;             const bool last = (t == nt - 2);
;             const char* a1 = cA + (size_t)(t + 1) * kstep;
;             const char* a2 = last ? nA : cA + (size_t)(t + 2) * kstep; const char* b2 = last ? nB : cB + (size_t)(t + 2) * kstep;
;             const char* a3 = a2 + kstep; const char* b3 = b2 + kstep;
;     ...
; #pragma unroll
;         for (int a = 0; a < 2; ++a)
; #pragma unroll
;             for (int b = 0; b < 2; ++b)
; #pragma unroll
;                 for (int m = 0; m < 4; ++m)
; #pragma unroll
;                     for (int n = 0; n < 2; ++n) acc[a][b][m][n] = (f32x4){0.f, 0.f, 0.f, 0.f};
;         cur = nxt; cA = nA; cB = nB; ++ui;
.LBB0_522:
	v_mov_b32_e32 v129, 0
	s_andn2_b64 vcc, exec, s[16:17]
	v_mov_b32_e32 v128, v129
	v_mov_b32_e32 v127, v129
	v_mov_b32_e32 v126, v129
	v_mov_b32_e32 v125, v129
	v_mov_b32_e32 v124, v129
	v_mov_b32_e32 v123, v129
	v_mov_b32_e32 v122, v129
	v_mov_b32_e32 v113, v129
	v_mov_b32_e32 v112, v129
	v_mov_b32_e32 v111, v129
	v_mov_b32_e32 v110, v129
	v_mov_b32_e32 v109, v129
	v_mov_b32_e32 v108, v129
	v_mov_b32_e32 v107, v129
	v_mov_b32_e32 v106, v129
	v_mov_b32_e32 v97, v129
	v_mov_b32_e32 v96, v129
	v_mov_b32_e32 v95, v129
	v_mov_b32_e32 v94, v129
	v_mov_b32_e32 v93, v129
	v_mov_b32_e32 v92, v129
	v_mov_b32_e32 v91, v129
	v_mov_b32_e32 v90, v129
	v_mov_b32_e32 v81, v129
	v_mov_b32_e32 v80, v129
	v_mov_b32_e32 v79, v129
	v_mov_b32_e32 v78, v129
	v_mov_b32_e32 v77, v129
	v_mov_b32_e32 v76, v129
	v_mov_b32_e32 v75, v129
	v_mov_b32_e32 v74, v129
	v_mov_b32_e32 v121, v129
	v_mov_b32_e32 v120, v129
	v_mov_b32_e32 v119, v129
	v_mov_b32_e32 v118, v129
	v_mov_b32_e32 v117, v129
	v_mov_b32_e32 v116, v129
	v_mov_b32_e32 v115, v129
	v_mov_b32_e32 v114, v129
	v_mov_b32_e32 v105, v129
	v_mov_b32_e32 v104, v129
	v_mov_b32_e32 v103, v129
	v_mov_b32_e32 v102, v129
	v_mov_b32_e32 v101, v129
	v_mov_b32_e32 v100, v129
	v_mov_b32_e32 v99, v129
	v_mov_b32_e32 v98, v129
	v_mov_b32_e32 v89, v129
	v_mov_b32_e32 v88, v129
	v_mov_b32_e32 v87, v129
	v_mov_b32_e32 v86, v129
	v_mov_b32_e32 v85, v129
	v_mov_b32_e32 v84, v129
	v_mov_b32_e32 v83, v129
	v_mov_b32_e32 v82, v129
	v_mov_b32_e32 v73, v129
	v_mov_b32_e32 v72, v129
	v_mov_b32_e32 v71, v129
	v_mov_b32_e32 v70, v129
	v_mov_b32_e32 v69, v129
	v_mov_b32_e32 v68, v129
	v_mov_b32_e32 v67, v129
	v_mov_b32_e32 v66, v129
	v_mov_b32_e32 v65, v129
	v_mov_b32_e32 v64, v129
	v_mov_b32_e32 v63, v129
	v_mov_b32_e32 v62, v129
	v_mov_b32_e32 v61, v129
	v_mov_b32_e32 v60, v129
	v_mov_b32_e32 v59, v129
	v_mov_b32_e32 v58, v129
	v_mov_b32_e32 v49, v129
	v_mov_b32_e32 v48, v129
	v_mov_b32_e32 v47, v129
	v_mov_b32_e32 v46, v129
	v_mov_b32_e32 v45, v129
	v_mov_b32_e32 v44, v129
	v_mov_b32_e32 v43, v129
	v_mov_b32_e32 v42, v129
	v_mov_b32_e32 v33, v129
	v_mov_b32_e32 v32, v129
	v_mov_b32_e32 v31, v129
	v_mov_b32_e32 v30, v129
	v_mov_b32_e32 v29, v129
	v_mov_b32_e32 v28, v129
	v_mov_b32_e32 v27, v129
	v_mov_b32_e32 v26, v129
	v_mov_b32_e32 v17, v129
	v_mov_b32_e32 v16, v129
	v_mov_b32_e32 v15, v129
	v_mov_b32_e32 v14, v129
	v_mov_b32_e32 v13, v129
	v_mov_b32_e32 v12, v129
	v_mov_b32_e32 v11, v129
	v_mov_b32_e32 v10, v129
	v_mov_b32_e32 v57, v129
	v_mov_b32_e32 v56, v129
	v_mov_b32_e32 v55, v129
	v_mov_b32_e32 v54, v129
	v_mov_b32_e32 v53, v129
	v_mov_b32_e32 v52, v129
	v_mov_b32_e32 v51, v129
	v_mov_b32_e32 v50, v129
	v_mov_b32_e32 v41, v129
	v_mov_b32_e32 v40, v129
	v_mov_b32_e32 v39, v129
	v_mov_b32_e32 v38, v129
	v_mov_b32_e32 v37, v129
	v_mov_b32_e32 v36, v129
	v_mov_b32_e32 v35, v129
	v_mov_b32_e32 v34, v129
	v_mov_b32_e32 v25, v129
	v_mov_b32_e32 v24, v129
	v_mov_b32_e32 v23, v129
	v_mov_b32_e32 v22, v129
	v_mov_b32_e32 v21, v129
	v_mov_b32_e32 v20, v129
	v_mov_b32_e32 v19, v129
	v_mov_b32_e32 v18, v129
	v_mov_b32_e32 v9, v129
	v_mov_b32_e32 v8, v129
	v_mov_b32_e32 v7, v129
	v_mov_b32_e32 v6, v129
	v_mov_b32_e32 v5, v129
	v_mov_b32_e32 v4, v129
	v_mov_b32_e32 v3, v129
	v_mov_b32_e32 v2, v129
	s_cbranch_vccnz .LBB0_526
	s_add_u32 s22, s22, 0x80
	s_addc_u32 s23, s23, 0
	s_add_u32 s39, s26, 0x100
	v_mov_b32_e32 v2, 0
	s_addc_u32 s40, s27, 0
	s_mov_b32 s3, 0
	v_mov_b32_e32 v3, v2
	v_mov_b32_e32 v4, v2
	v_mov_b32_e32 v5, v2
	v_mov_b32_e32 v6, v2
	v_mov_b32_e32 v7, v2
	v_mov_b32_e32 v8, v2
	v_mov_b32_e32 v9, v2
	v_mov_b32_e32 v18, v2
	v_mov_b32_e32 v19, v2
	v_mov_b32_e32 v20, v2
	v_mov_b32_e32 v21, v2
	v_mov_b32_e32 v22, v2
	v_mov_b32_e32 v23, v2
	v_mov_b32_e32 v24, v2
	v_mov_b32_e32 v25, v2
	v_mov_b32_e32 v34, v2
	v_mov_b32_e32 v35, v2
	v_mov_b32_e32 v36, v2
	v_mov_b32_e32 v37, v2
	v_mov_b32_e32 v38, v2
	v_mov_b32_e32 v39, v2
	v_mov_b32_e32 v40, v2
	v_mov_b32_e32 v41, v2
	v_mov_b32_e32 v50, v2
	v_mov_b32_e32 v51, v2
	v_mov_b32_e32 v52, v2
	v_mov_b32_e32 v53, v2
	v_mov_b32_e32 v54, v2
	v_mov_b32_e32 v55, v2
	v_mov_b32_e32 v56, v2
	v_mov_b32_e32 v57, v2
	v_mov_b32_e32 v10, v2
	v_mov_b32_e32 v11, v2
	v_mov_b32_e32 v12, v2
	v_mov_b32_e32 v13, v2
	v_mov_b32_e32 v14, v2
	v_mov_b32_e32 v15, v2
	v_mov_b32_e32 v16, v2
	v_mov_b32_e32 v17, v2
	v_mov_b32_e32 v26, v2
	v_mov_b32_e32 v27, v2
	v_mov_b32_e32 v28, v2
	v_mov_b32_e32 v29, v2
	v_mov_b32_e32 v30, v2
	v_mov_b32_e32 v31, v2
	v_mov_b32_e32 v32, v2
	v_mov_b32_e32 v33, v2
	v_mov_b32_e32 v42, v2
	v_mov_b32_e32 v43, v2
	v_mov_b32_e32 v44, v2
	v_mov_b32_e32 v45, v2
	v_mov_b32_e32 v46, v2
	v_mov_b32_e32 v47, v2
	v_mov_b32_e32 v48, v2
	v_mov_b32_e32 v49, v2
	v_mov_b32_e32 v58, v2
	v_mov_b32_e32 v59, v2
	v_mov_b32_e32 v60, v2
	v_mov_b32_e32 v61, v2
	v_mov_b32_e32 v62, v2
	v_mov_b32_e32 v63, v2
	v_mov_b32_e32 v64, v2
	v_mov_b32_e32 v65, v2
	v_mov_b32_e32 v66, v2
	v_mov_b32_e32 v67, v2
	v_mov_b32_e32 v68, v2
	v_mov_b32_e32 v69, v2
	v_mov_b32_e32 v70, v2
	v_mov_b32_e32 v71, v2
	v_mov_b32_e32 v72, v2
	v_mov_b32_e32 v73, v2
	v_mov_b32_e32 v82, v2
	v_mov_b32_e32 v83, v2
	v_mov_b32_e32 v84, v2
	v_mov_b32_e32 v85, v2
	v_mov_b32_e32 v86, v2
	v_mov_b32_e32 v87, v2
	v_mov_b32_e32 v88, v2
	v_mov_b32_e32 v89, v2
	v_mov_b32_e32 v98, v2
	v_mov_b32_e32 v99, v2
	v_mov_b32_e32 v100, v2
	v_mov_b32_e32 v101, v2
	v_mov_b32_e32 v102, v2
	v_mov_b32_e32 v103, v2
	v_mov_b32_e32 v104, v2
	v_mov_b32_e32 v105, v2
	v_mov_b32_e32 v114, v2
	v_mov_b32_e32 v115, v2
	v_mov_b32_e32 v116, v2
	v_mov_b32_e32 v117, v2
	v_mov_b32_e32 v118, v2
	v_mov_b32_e32 v119, v2
	v_mov_b32_e32 v120, v2
	v_mov_b32_e32 v121, v2
	v_mov_b32_e32 v74, v2
	v_mov_b32_e32 v75, v2
	v_mov_b32_e32 v76, v2
	v_mov_b32_e32 v77, v2
	v_mov_b32_e32 v78, v2
	v_mov_b32_e32 v79, v2
	v_mov_b32_e32 v80, v2
	v_mov_b32_e32 v81, v2
	v_mov_b32_e32 v90, v2
	v_mov_b32_e32 v91, v2
	v_mov_b32_e32 v92, v2
	v_mov_b32_e32 v93, v2
	v_mov_b32_e32 v94, v2
	v_mov_b32_e32 v95, v2
	v_mov_b32_e32 v96, v2
	v_mov_b32_e32 v97, v2
	v_mov_b32_e32 v106, v2
	v_mov_b32_e32 v107, v2
	v_mov_b32_e32 v108, v2
	v_mov_b32_e32 v109, v2
	v_mov_b32_e32 v110, v2
	v_mov_b32_e32 v111, v2
	v_mov_b32_e32 v112, v2
	v_mov_b32_e32 v113, v2
	v_mov_b32_e32 v122, v2
	v_mov_b32_e32 v123, v2
	v_mov_b32_e32 v124, v2
	v_mov_b32_e32 v125, v2
	v_mov_b32_e32 v126, v2
	v_mov_b32_e32 v127, v2
	v_mov_b32_e32 v128, v2
	v_mov_b32_e32 v129, v2
	s_nop 0

; template <class Epi, class Sched, bool ALIGN_EPI = false, bool SP2 = false, bool GRP = false>
; __device__ __forceinline__ void gemm_phase(PG8_LAS unsigned char* lds, const Gemm g, const Sched& S, const Epi& E) {
;     ...
;         for (int t = 0; t < nt; t += 2) {
;             const bool last = (t == nt - 2);
;             const char* a1 = cA + (size_t)(t + 1) * kstep;
;             const char* a2 = last ? nA : cA + (size_t)(t + 2) * kstep; const char* b2 = last ? nB : cB + (size_t)(t + 2) * kstep;
;             const char* a3 = a2 + kstep; const char* b3 = b2 + kstep;
;     ...
; #pragma unroll
;         for (int a = 0; a < 2; ++a)
; #pragma unroll
;             for (int b = 0; b < 2; ++b)
; #pragma unroll
;                 for (int m = 0; m < 4; ++m)
; #pragma unroll
;                     for (int n = 0; n < 2; ++n) acc[a][b][m][n] = (f32x4){0.f, 0.f, 0.f, 0.f};
;         cur = nxt; cA = nA; cB = nB; ++ui;
.LBB0_705:
	v_mov_b32_e32 v129, 0
	s_andn2_b64 vcc, exec, s[22:23]
	v_mov_b32_e32 v128, v129
	v_mov_b32_e32 v127, v129
	v_mov_b32_e32 v126, v129
	v_mov_b32_e32 v125, v129
	v_mov_b32_e32 v124, v129
	v_mov_b32_e32 v123, v129
	v_mov_b32_e32 v122, v129
	v_mov_b32_e32 v113, v129
	v_mov_b32_e32 v112, v129
	v_mov_b32_e32 v111, v129
	v_mov_b32_e32 v110, v129
	v_mov_b32_e32 v109, v129
	v_mov_b32_e32 v108, v129
	v_mov_b32_e32 v107, v129
	v_mov_b32_e32 v106, v129
	v_mov_b32_e32 v97, v129
	v_mov_b32_e32 v96, v129
	v_mov_b32_e32 v95, v129
	v_mov_b32_e32 v94, v129
	v_mov_b32_e32 v93, v129
	v_mov_b32_e32 v92, v129
	v_mov_b32_e32 v91, v129
	v_mov_b32_e32 v90, v129
	v_mov_b32_e32 v81, v129
	v_mov_b32_e32 v80, v129
	v_mov_b32_e32 v79, v129
	v_mov_b32_e32 v78, v129
	v_mov_b32_e32 v77, v129
	v_mov_b32_e32 v76, v129
	v_mov_b32_e32 v75, v129
	v_mov_b32_e32 v74, v129
	v_mov_b32_e32 v121, v129
	v_mov_b32_e32 v120, v129
	v_mov_b32_e32 v119, v129
	v_mov_b32_e32 v118, v129
	v_mov_b32_e32 v117, v129
	v_mov_b32_e32 v116, v129
	v_mov_b32_e32 v115, v129
	v_mov_b32_e32 v114, v129
	v_mov_b32_e32 v105, v129
	v_mov_b32_e32 v104, v129
	v_mov_b32_e32 v103, v129
	v_mov_b32_e32 v102, v129
	v_mov_b32_e32 v101, v129
	v_mov_b32_e32 v100, v129
	v_mov_b32_e32 v99, v129
	v_mov_b32_e32 v98, v129
	v_mov_b32_e32 v89, v129
	v_mov_b32_e32 v88, v129
	v_mov_b32_e32 v87, v129
	v_mov_b32_e32 v86, v129
	v_mov_b32_e32 v85, v129
	v_mov_b32_e32 v84, v129
	v_mov_b32_e32 v83, v129
	v_mov_b32_e32 v82, v129
	v_mov_b32_e32 v73, v129
	v_mov_b32_e32 v72, v129
	v_mov_b32_e32 v71, v129
	v_mov_b32_e32 v70, v129
	v_mov_b32_e32 v69, v129
	v_mov_b32_e32 v68, v129
	v_mov_b32_e32 v67, v129
	v_mov_b32_e32 v66, v129
	v_mov_b32_e32 v65, v129
	v_mov_b32_e32 v64, v129
	v_mov_b32_e32 v63, v129
	v_mov_b32_e32 v62, v129
	v_mov_b32_e32 v61, v129
	v_mov_b32_e32 v60, v129
	v_mov_b32_e32 v59, v129
	v_mov_b32_e32 v58, v129
	v_mov_b32_e32 v49, v129
	v_mov_b32_e32 v48, v129
	v_mov_b32_e32 v47, v129
	v_mov_b32_e32 v46, v129
	v_mov_b32_e32 v45, v129
	v_mov_b32_e32 v44, v129
	v_mov_b32_e32 v43, v129
	v_mov_b32_e32 v42, v129
	v_mov_b32_e32 v33, v129
	v_mov_b32_e32 v32, v129
	v_mov_b32_e32 v31, v129
	v_mov_b32_e32 v30, v129
	v_mov_b32_e32 v29, v129
	v_mov_b32_e32 v28, v129
	v_mov_b32_e32 v27, v129
	v_mov_b32_e32 v26, v129
	v_mov_b32_e32 v17, v129
	v_mov_b32_e32 v16, v129
	v_mov_b32_e32 v15, v129
	v_mov_b32_e32 v14, v129
	v_mov_b32_e32 v13, v129
	v_mov_b32_e32 v12, v129
	v_mov_b32_e32 v11, v129
	v_mov_b32_e32 v10, v129
	v_mov_b32_e32 v57, v129
	v_mov_b32_e32 v56, v129
	v_mov_b32_e32 v55, v129
	v_mov_b32_e32 v54, v129
	v_mov_b32_e32 v53, v129
	v_mov_b32_e32 v52, v129
	v_mov_b32_e32 v51, v129
	v_mov_b32_e32 v50, v129
	v_mov_b32_e32 v41, v129
	v_mov_b32_e32 v40, v129
	v_mov_b32_e32 v39, v129
	v_mov_b32_e32 v38, v129
	v_mov_b32_e32 v37, v129
	v_mov_b32_e32 v36, v129
	v_mov_b32_e32 v35, v129
	v_mov_b32_e32 v34, v129
	v_mov_b32_e32 v25, v129
	v_mov_b32_e32 v24, v129
	v_mov_b32_e32 v23, v129
	v_mov_b32_e32 v22, v129
	v_mov_b32_e32 v21, v129
	v_mov_b32_e32 v20, v129
	v_mov_b32_e32 v19, v129
	v_mov_b32_e32 v18, v129
	v_mov_b32_e32 v9, v129
	v_mov_b32_e32 v8, v129
	v_mov_b32_e32 v7, v129
	v_mov_b32_e32 v6, v129
	v_mov_b32_e32 v5, v129
	v_mov_b32_e32 v4, v129
	v_mov_b32_e32 v3, v129
	v_mov_b32_e32 v2, v129
	s_cbranch_vccnz .LBB0_708
	s_add_u32 s70, s70, 0x80
	s_addc_u32 s71, s71, 0
	s_add_u32 s25, s72, 0x100
	v_mov_b32_e32 v2, 0
	s_addc_u32 s33, s73, 0
	s_mov_b32 s3, 0
	v_mov_b32_e32 v3, v2
	v_mov_b32_e32 v4, v2
	v_mov_b32_e32 v5, v2
	v_mov_b32_e32 v6, v2
	v_mov_b32_e32 v7, v2
	v_mov_b32_e32 v8, v2
	v_mov_b32_e32 v9, v2
	v_mov_b32_e32 v18, v2
	v_mov_b32_e32 v19, v2
	v_mov_b32_e32 v20, v2
	v_mov_b32_e32 v21, v2
	v_mov_b32_e32 v22, v2
	v_mov_b32_e32 v23, v2
	v_mov_b32_e32 v24, v2
	v_mov_b32_e32 v25, v2
	v_mov_b32_e32 v34, v2
	v_mov_b32_e32 v35, v2
	v_mov_b32_e32 v36, v2
	v_mov_b32_e32 v37, v2
	v_mov_b32_e32 v38, v2
	v_mov_b32_e32 v39, v2
	v_mov_b32_e32 v40, v2
	v_mov_b32_e32 v41, v2
	v_mov_b32_e32 v50, v2
	v_mov_b32_e32 v51, v2
	v_mov_b32_e32 v52, v2
	v_mov_b32_e32 v53, v2
	v_mov_b32_e32 v54, v2
	v_mov_b32_e32 v55, v2
	v_mov_b32_e32 v56, v2
	v_mov_b32_e32 v57, v2
	v_mov_b32_e32 v10, v2
	v_mov_b32_e32 v11, v2
	v_mov_b32_e32 v12, v2
	v_mov_b32_e32 v13, v2
	v_mov_b32_e32 v14, v2
	v_mov_b32_e32 v15, v2
	v_mov_b32_e32 v16, v2
	v_mov_b32_e32 v17, v2
	v_mov_b32_e32 v26, v2
	v_mov_b32_e32 v27, v2
	v_mov_b32_e32 v28, v2
	v_mov_b32_e32 v29, v2
	v_mov_b32_e32 v30, v2
	v_mov_b32_e32 v31, v2
	v_mov_b32_e32 v32, v2
	v_mov_b32_e32 v33, v2
	v_mov_b32_e32 v42, v2
	v_mov_b32_e32 v43, v2
	v_mov_b32_e32 v44, v2
	v_mov_b32_e32 v45, v2
	v_mov_b32_e32 v46, v2
	v_mov_b32_e32 v47, v2
	v_mov_b32_e32 v48, v2
	v_mov_b32_e32 v49, v2
	v_mov_b32_e32 v58, v2
	v_mov_b32_e32 v59, v2
	v_mov_b32_e32 v60, v2
	v_mov_b32_e32 v61, v2
	v_mov_b32_e32 v62, v2
	v_mov_b32_e32 v63, v2
	v_mov_b32_e32 v64, v2
	v_mov_b32_e32 v65, v2
	v_mov_b32_e32 v66, v2
	v_mov_b32_e32 v67, v2
	v_mov_b32_e32 v68, v2
	v_mov_b32_e32 v69, v2
	v_mov_b32_e32 v70, v2
	v_mov_b32_e32 v71, v2
	v_mov_b32_e32 v72, v2
	v_mov_b32_e32 v73, v2
	v_mov_b32_e32 v82, v2
	v_mov_b32_e32 v83, v2
	v_mov_b32_e32 v84, v2
	v_mov_b32_e32 v85, v2
	v_mov_b32_e32 v86, v2
	v_mov_b32_e32 v87, v2
	v_mov_b32_e32 v88, v2
	v_mov_b32_e32 v89, v2
	v_mov_b32_e32 v98, v2
	v_mov_b32_e32 v99, v2
	v_mov_b32_e32 v100, v2
	v_mov_b32_e32 v101, v2
	v_mov_b32_e32 v102, v2
	v_mov_b32_e32 v103, v2
	v_mov_b32_e32 v104, v2
	v_mov_b32_e32 v105, v2
	v_mov_b32_e32 v114, v2
	v_mov_b32_e32 v115, v2
	v_mov_b32_e32 v116, v2
	v_mov_b32_e32 v117, v2
	v_mov_b32_e32 v118, v2
	v_mov_b32_e32 v119, v2
	v_mov_b32_e32 v120, v2
	v_mov_b32_e32 v121, v2
	v_mov_b32_e32 v74, v2
	v_mov_b32_e32 v75, v2
	v_mov_b32_e32 v76, v2
	v_mov_b32_e32 v77, v2
	v_mov_b32_e32 v78, v2
	v_mov_b32_e32 v79, v2
	v_mov_b32_e32 v80, v2
	v_mov_b32_e32 v81, v2
	v_mov_b32_e32 v90, v2
	v_mov_b32_e32 v91, v2
	v_mov_b32_e32 v92, v2
	v_mov_b32_e32 v93, v2
	v_mov_b32_e32 v94, v2
	v_mov_b32_e32 v95, v2
	v_mov_b32_e32 v96, v2
	v_mov_b32_e32 v97, v2
	v_mov_b32_e32 v106, v2
	v_mov_b32_e32 v107, v2
	v_mov_b32_e32 v108, v2
	v_mov_b32_e32 v109, v2
	v_mov_b32_e32 v110, v2
	v_mov_b32_e32 v111, v2
	v_mov_b32_e32 v112, v2
	v_mov_b32_e32 v113, v2
	v_mov_b32_e32 v122, v2
	v_mov_b32_e32 v123, v2
	v_mov_b32_e32 v124, v2
	v_mov_b32_e32 v125, v2
	v_mov_b32_e32 v126, v2
	v_mov_b32_e32 v127, v2
	v_mov_b32_e32 v128, v2
	v_mov_b32_e32 v129, v2
	s_nop 0

; template <class Epi, class Sched, bool ALIGN_EPI = false, bool SP2 = false, bool GRP = false>
; __device__ __forceinline__ void gemm_phase(PG8_LAS unsigned char* lds, const Gemm g, const Sched& S, const Epi& E) {
;     ...
;         for (int t = 0; t < nt; t += 2) {
;             const bool last = (t == nt - 2);
;             const char* a1 = cA + (size_t)(t + 1) * kstep;
;             const char* a2 = last ? nA : cA + (size_t)(t + 2) * kstep; const char* b2 = last ? nB : cB + (size_t)(t + 2) * kstep;
;             const char* a3 = a2 + kstep; const char* b3 = b2 + kstep;
.LBB0_800:
	s_add_u32 s80, s74, 0x80
	s_addc_u32 s81, s75, 0
	s_add_u32 s55, s72, 0x100
	s_addc_u32 s92, s73, 0
	s_mov_b32 s82, 0
	s_nop 0

; template <class Epi, class Sched, bool ALIGN_EPI = false, bool SP2 = false, bool GRP = false>
; __device__ __forceinline__ void gemm_phase(PG8_LAS unsigned char* lds, const Gemm g, const Sched& S, const Epi& E) {
;     ...
;         for (int t = 0; t < nt; t += 2) {
;             const bool last = (t == nt - 2);
;             const char* a1 = cA + (size_t)(t + 1) * kstep;
;             const char* a2 = last ? nA : cA + (size_t)(t + 2) * kstep; const char* b2 = last ? nB : cB + (size_t)(t + 2) * kstep;
;             const char* a3 = a2 + kstep; const char* b3 = b2 + kstep;
.LBB0_885:
	s_add_u32 s82, s76, 0x80
	s_addc_u32 s83, s77, 0
	s_add_u32 s55, s74, 0x100
	s_addc_u32 s96, s75, 0
	s_mov_b32 s84, 0
	s_nop 0

; template <class Epi, class Sched, bool ALIGN_EPI = false, bool SP2 = false, bool GRP = false>
; __device__ __forceinline__ void gemm_phase(PG8_LAS unsigned char* lds, const Gemm g, const Sched& S, const Epi& E) {
;     ...
;         for (int t = 0; t < nt; t += 2) {
;             const bool last = (t == nt - 2);
;             const char* a1 = cA + (size_t)(t + 1) * kstep;
;             const char* a2 = last ? nA : cA + (size_t)(t + 2) * kstep; const char* b2 = last ? nB : cB + (size_t)(t + 2) * kstep;
;             const char* a3 = a2 + kstep; const char* b3 = b2 + kstep;
.LBB0_1189:
	s_add_u32 s82, s76, 0x80
	s_addc_u32 s83, s77, 0
	s_add_u32 vcc_lo, s74, 0x100
	s_addc_u32 vcc_hi, s75, 0
	s_mov_b32 s84, 0
	s_nop 0
